# s_setprio pairs removed from the three GEMM main loops (A/B test)
# speedup vs baseline: 1.0131x; 1.0131x over previous
.LBB0_75:
	s_add_u32 s68, s90, 0xfffc0080
	s_addc_u32 s69, s91, -1
	s_add_i32 s70, 0, 0x10000
	s_cmp_eq_u32 s97, 12
	s_cselect_b32 s95, s2, s69
	s_cselect_b32 s94, s6, s68
	v_add_u32_e32 v140, s70, v151
	s_cselect_b32 s93, s51, s96
	s_cselect_b32 s92, s63, s89
	s_add_i32 s71, 0, 0x14000
	s_waitcnt vmcnt(0)
	ds_read_b128 v[154:157], v140
	ds_read_b128 v[158:161], v140 offset:1024
	ds_read_b128 v[162:165], v140 offset:2048
	ds_read_b128 v[166:169], v140 offset:3072
	v_add_u32_e32 v140, s71, v151
	ds_read_b128 v[170:173], v140
	ds_read_b128 v[174:177], v140 offset:1024
	ds_read_b128 v[178:181], v140 offset:2048
	ds_read_b128 v[182:185], v140 offset:3072
	v_lshl_add_u64 v[140:141], s[90:91], 0, v[136:137]
	s_add_i32 m0, s18, 0xc000
	ds_read_b128 v[186:189], v153
	ds_read_b128 v[190:193], v153 offset:1024
	ds_read_b128 v[194:197], v153 offset:2048
	ds_read_b128 v[198:201], v153 offset:3072
	ds_read_b128 v[202:205], v153 offset:4096
	ds_read_b128 v[210:213], v153 offset:5120
	ds_read_b128 v[214:217], v153 offset:6144
	ds_read_b128 v[218:221], v153 offset:7168
	global_load_lds_dwordx4 v[140:141], off
	v_lshl_add_u64 v[140:141], s[90:91], 0, v[138:139]
	s_add_i32 m0, s18, 0xe000
	s_nop 0
	global_load_lds_dwordx4 v[140:141], off
	s_waitcnt vmcnt(8)
	s_waitcnt lgkmcnt(0)
	s_barrier
	s_waitcnt lgkmcnt(0)
	v_mfma_f32_16x16x32_bf16 v[126:129], v[154:157], v[186:189], v[126:129]
	v_mfma_f32_16x16x32_bf16 v[122:125], v[162:165], v[186:189], v[122:125]
	v_mfma_f32_16x16x32_bf16 v[110:113], v[154:157], v[194:197], v[110:113]
	v_mfma_f32_16x16x32_bf16 v[106:109], v[162:165], v[194:197], v[106:109]
	v_mfma_f32_16x16x32_bf16 v[98:101], v[154:157], v[202:205], v[98:101]
	v_mfma_f32_16x16x32_bf16 v[90:93], v[162:165], v[202:205], v[90:93]
	v_mfma_f32_16x16x32_bf16 v[82:85], v[154:157], v[214:217], v[82:85]
	v_mfma_f32_16x16x32_bf16 v[74:77], v[162:165], v[214:217], v[74:77]
	v_mfma_f32_16x16x32_bf16 v[118:121], v[170:173], v[186:189], v[118:121]
	v_mfma_f32_16x16x32_bf16 v[114:117], v[178:181], v[186:189], v[114:117]
	v_mfma_f32_16x16x32_bf16 v[102:105], v[170:173], v[194:197], v[102:105]
	v_mfma_f32_16x16x32_bf16 v[94:97], v[178:181], v[194:197], v[94:97]
	v_mfma_f32_16x16x32_bf16 v[86:89], v[170:173], v[202:205], v[86:89]
	v_mfma_f32_16x16x32_bf16 v[78:81], v[178:181], v[202:205], v[78:81]
	v_mfma_f32_16x16x32_bf16 v[70:73], v[170:173], v[214:217], v[70:73]
	v_mfma_f32_16x16x32_bf16 v[66:69], v[178:181], v[214:217], v[66:69]
	v_mfma_f32_16x16x32_bf16 v[126:129], v[158:161], v[190:193], v[126:129]
	v_mfma_f32_16x16x32_bf16 v[122:125], v[166:169], v[190:193], v[122:125]
	v_mfma_f32_16x16x32_bf16 v[110:113], v[158:161], v[198:201], v[110:113]
	v_mfma_f32_16x16x32_bf16 v[106:109], v[166:169], v[198:201], v[106:109]
	v_mfma_f32_16x16x32_bf16 v[98:101], v[158:161], v[210:213], v[98:101]
	v_mfma_f32_16x16x32_bf16 v[90:93], v[166:169], v[210:213], v[90:93]
	v_mfma_f32_16x16x32_bf16 v[82:85], v[158:161], v[218:221], v[82:85]
	v_mfma_f32_16x16x32_bf16 v[74:77], v[166:169], v[218:221], v[74:77]
	v_mfma_f32_16x16x32_bf16 v[118:121], v[174:177], v[190:193], v[118:121]
	v_mfma_f32_16x16x32_bf16 v[114:117], v[182:185], v[190:193], v[114:117]
	v_mfma_f32_16x16x32_bf16 v[102:105], v[174:177], v[198:201], v[102:105]
	v_mfma_f32_16x16x32_bf16 v[94:97], v[182:185], v[198:201], v[94:97]
	v_mfma_f32_16x16x32_bf16 v[86:89], v[174:177], v[210:213], v[86:89]
	v_mfma_f32_16x16x32_bf16 v[78:81], v[182:185], v[210:213], v[78:81]
	v_mfma_f32_16x16x32_bf16 v[70:73], v[174:177], v[218:221], v[70:73]
	v_mfma_f32_16x16x32_bf16 v[66:69], v[182:185], v[218:221], v[66:69]
	s_barrier
	s_add_i32 s68, s70, s16
	v_lshl_add_u64 v[140:141], s[92:93], 0, v[0:1]
	s_mov_b32 m0, s68
	ds_read_b128 v[186:189], v153 offset:16384
	ds_read_b128 v[190:193], v153 offset:17408
	ds_read_b128 v[194:197], v153 offset:18432
	ds_read_b128 v[198:201], v153 offset:19456
	ds_read_b128 v[202:205], v153 offset:20480
	ds_read_b128 v[210:213], v153 offset:21504
	ds_read_b128 v[214:217], v153 offset:22528
	ds_read_b128 v[218:221], v153 offset:23552
	global_load_lds_dwordx4 v[140:141], off
	s_add_i32 m0, s68, 0x2000
	s_add_u32 s68, s92, 0x40000
	v_lshl_add_u64 v[144:145], s[92:93], 0, v[130:131]
	s_addc_u32 s69, s93, 0
	s_add_i32 s70, s71, s16
	global_load_lds_dwordx4 v[144:145], off
	v_lshl_add_u64 v[148:149], s[68:69], 0, v[0:1]
	s_mov_b32 m0, s70
	v_lshl_add_u64 v[206:207], s[94:95], 0, v[132:133]
	global_load_lds_dwordx4 v[148:149], off
	v_lshl_add_u64 v[148:149], s[68:69], 0, v[130:131]
	s_add_i32 m0, s70, 0x2000
	s_nop 0
	global_load_lds_dwordx4 v[148:149], off
	v_lshl_add_u64 v[148:149], s[94:95], 0, v[134:135]
	s_mov_b32 m0, s18
	s_nop 0
	global_load_lds_dwordx4 v[148:149], off
	s_mov_b32 m0, s19
	s_nop 0
	global_load_lds_dwordx4 v[206:207], off
	s_waitcnt vmcnt(8)
	s_waitcnt lgkmcnt(0)
	s_barrier
	s_waitcnt lgkmcnt(0)
	v_mfma_f32_16x16x32_bf16 v[62:65], v[154:157], v[186:189], v[62:65]
	v_mfma_f32_16x16x32_bf16 v[58:61], v[162:165], v[186:189], v[58:61]
	v_mfma_f32_16x16x32_bf16 v[50:53], v[154:157], v[194:197], v[50:53]
	v_mfma_f32_16x16x32_bf16 v[42:45], v[162:165], v[194:197], v[42:45]
	v_mfma_f32_16x16x32_bf16 v[34:37], v[154:157], v[202:205], v[34:37]
	v_mfma_f32_16x16x32_bf16 v[26:29], v[162:165], v[202:205], v[26:29]
	v_mfma_f32_16x16x32_bf16 v[18:21], v[154:157], v[214:217], v[18:21]
	v_mfma_f32_16x16x32_bf16 v[10:13], v[162:165], v[214:217], v[10:13]
	v_mfma_f32_16x16x32_bf16 v[54:57], v[170:173], v[186:189], v[54:57]
	v_mfma_f32_16x16x32_bf16 v[46:49], v[178:181], v[186:189], v[46:49]
	v_mfma_f32_16x16x32_bf16 v[38:41], v[170:173], v[194:197], v[38:41]
	v_mfma_f32_16x16x32_bf16 v[30:33], v[178:181], v[194:197], v[30:33]
	v_mfma_f32_16x16x32_bf16 v[22:25], v[170:173], v[202:205], v[22:25]
	v_mfma_f32_16x16x32_bf16 v[14:17], v[178:181], v[202:205], v[14:17]
	v_mfma_f32_16x16x32_bf16 v[6:9], v[170:173], v[214:217], v[6:9]
	v_mfma_f32_16x16x32_bf16 v[2:5], v[178:181], v[214:217], v[2:5]
	v_mfma_f32_16x16x32_bf16 v[62:65], v[158:161], v[190:193], v[62:65]
	v_mfma_f32_16x16x32_bf16 v[58:61], v[166:169], v[190:193], v[58:61]
	v_mfma_f32_16x16x32_bf16 v[50:53], v[158:161], v[198:201], v[50:53]
	v_mfma_f32_16x16x32_bf16 v[42:45], v[166:169], v[198:201], v[42:45]
	v_mfma_f32_16x16x32_bf16 v[34:37], v[158:161], v[210:213], v[34:37]
	v_mfma_f32_16x16x32_bf16 v[26:29], v[166:169], v[210:213], v[26:29]
	v_mfma_f32_16x16x32_bf16 v[18:21], v[158:161], v[218:221], v[18:21]
	v_mfma_f32_16x16x32_bf16 v[10:13], v[166:169], v[218:221], v[10:13]
	v_mfma_f32_16x16x32_bf16 v[54:57], v[174:177], v[190:193], v[54:57]
	v_mfma_f32_16x16x32_bf16 v[46:49], v[182:185], v[190:193], v[46:49]
	v_mfma_f32_16x16x32_bf16 v[38:41], v[174:177], v[198:201], v[38:41]
	v_mfma_f32_16x16x32_bf16 v[30:33], v[182:185], v[198:201], v[30:33]
	v_mfma_f32_16x16x32_bf16 v[22:25], v[174:177], v[210:213], v[22:25]
	v_mfma_f32_16x16x32_bf16 v[14:17], v[182:185], v[210:213], v[14:17]
	v_mfma_f32_16x16x32_bf16 v[6:9], v[174:177], v[218:221], v[6:9]
	v_mfma_f32_16x16x32_bf16 v[2:5], v[182:185], v[218:221], v[2:5]
	s_barrier
	s_add_i32 s70, 0, 0x18000
	v_add_u32_e32 v142, s70, v151
	s_add_i32 s71, 0, 0x1c000
	ds_read_b128 v[154:157], v142
	ds_read_b128 v[158:161], v142 offset:1024
	ds_read_b128 v[162:165], v142 offset:2048
	ds_read_b128 v[166:169], v142 offset:3072
	v_add_u32_e32 v142, s71, v151
	ds_read_b128 v[170:173], v142
	ds_read_b128 v[174:177], v142 offset:1024
	ds_read_b128 v[178:181], v142 offset:2048
	ds_read_b128 v[182:185], v142 offset:3072
	s_add_u32 s68, s94, 0x40000
	s_addc_u32 s69, s95, 0
	s_mov_b32 m0, s20
	v_lshl_add_u64 v[222:223], s[68:69], 0, v[134:135]
	ds_read_b128 v[186:189], v153 offset:32768
	ds_read_b128 v[190:193], v153 offset:33792
	ds_read_b128 v[194:197], v153 offset:34816
	ds_read_b128 v[198:201], v153 offset:35840
	ds_read_b128 v[202:205], v153 offset:36864
	ds_read_b128 v[210:213], v153 offset:37888
	ds_read_b128 v[214:217], v153 offset:38912
	ds_read_b128 v[218:221], v153 offset:39936
	global_load_lds_dwordx4 v[222:223], off
	v_lshl_add_u64 v[222:223], s[68:69], 0, v[132:133]
	s_mov_b32 m0, s21
	s_nop 0
	global_load_lds_dwordx4 v[222:223], off
	s_waitcnt vmcnt(8)
	s_waitcnt lgkmcnt(0)
	s_barrier
	s_waitcnt lgkmcnt(0)
	v_mfma_f32_16x16x32_bf16 v[126:129], v[154:157], v[186:189], v[126:129]
	v_mfma_f32_16x16x32_bf16 v[122:125], v[162:165], v[186:189], v[122:125]
	v_mfma_f32_16x16x32_bf16 v[110:113], v[154:157], v[194:197], v[110:113]
	v_mfma_f32_16x16x32_bf16 v[106:109], v[162:165], v[194:197], v[106:109]
	v_mfma_f32_16x16x32_bf16 v[98:101], v[154:157], v[202:205], v[98:101]
	v_mfma_f32_16x16x32_bf16 v[90:93], v[162:165], v[202:205], v[90:93]
	v_mfma_f32_16x16x32_bf16 v[82:85], v[154:157], v[214:217], v[82:85]
	v_mfma_f32_16x16x32_bf16 v[74:77], v[162:165], v[214:217], v[74:77]
	v_mfma_f32_16x16x32_bf16 v[118:121], v[170:173], v[186:189], v[118:121]
	v_mfma_f32_16x16x32_bf16 v[114:117], v[178:181], v[186:189], v[114:117]
	v_mfma_f32_16x16x32_bf16 v[102:105], v[170:173], v[194:197], v[102:105]
	v_mfma_f32_16x16x32_bf16 v[94:97], v[178:181], v[194:197], v[94:97]
	v_mfma_f32_16x16x32_bf16 v[86:89], v[170:173], v[202:205], v[86:89]
	v_mfma_f32_16x16x32_bf16 v[78:81], v[178:181], v[202:205], v[78:81]
	v_mfma_f32_16x16x32_bf16 v[70:73], v[170:173], v[214:217], v[70:73]
	v_mfma_f32_16x16x32_bf16 v[66:69], v[178:181], v[214:217], v[66:69]
	v_mfma_f32_16x16x32_bf16 v[126:129], v[158:161], v[190:193], v[126:129]
	v_mfma_f32_16x16x32_bf16 v[122:125], v[166:169], v[190:193], v[122:125]
	v_mfma_f32_16x16x32_bf16 v[110:113], v[158:161], v[198:201], v[110:113]
	v_mfma_f32_16x16x32_bf16 v[106:109], v[166:169], v[198:201], v[106:109]
	v_mfma_f32_16x16x32_bf16 v[98:101], v[158:161], v[210:213], v[98:101]
	v_mfma_f32_16x16x32_bf16 v[90:93], v[166:169], v[210:213], v[90:93]
	v_mfma_f32_16x16x32_bf16 v[82:85], v[158:161], v[218:221], v[82:85]
	v_mfma_f32_16x16x32_bf16 v[74:77], v[166:169], v[218:221], v[74:77]
	v_mfma_f32_16x16x32_bf16 v[118:121], v[174:177], v[190:193], v[118:121]
	v_mfma_f32_16x16x32_bf16 v[114:117], v[182:185], v[190:193], v[114:117]
	v_mfma_f32_16x16x32_bf16 v[102:105], v[174:177], v[198:201], v[102:105]
	v_mfma_f32_16x16x32_bf16 v[94:97], v[182:185], v[198:201], v[94:97]
	v_mfma_f32_16x16x32_bf16 v[86:89], v[174:177], v[210:213], v[86:89]
	v_mfma_f32_16x16x32_bf16 v[78:81], v[182:185], v[210:213], v[78:81]
	v_mfma_f32_16x16x32_bf16 v[70:73], v[174:177], v[218:221], v[70:73]
	v_mfma_f32_16x16x32_bf16 v[66:69], v[182:185], v[218:221], v[66:69]
	s_barrier
	s_add_i32 s68, s70, s16
	v_lshl_add_u64 v[140:141], v[140:141], 0, s[34:35]
	s_mov_b32 m0, s68
	ds_read_b128 v[186:189], v153 offset:49152
	ds_read_b128 v[190:193], v153 offset:50176
	ds_read_b128 v[194:197], v153 offset:51200
	ds_read_b128 v[198:201], v153 offset:52224
	ds_read_b128 v[202:205], v153 offset:53248
	ds_read_b128 v[210:213], v153 offset:54272
	ds_read_b128 v[214:217], v153 offset:55296
	ds_read_b128 v[218:221], v153 offset:56320
	global_load_lds_dwordx4 v[140:141], off
	s_add_i32 m0, s68, 0x2000
	s_add_u32 s68, s92, 0x40080
	v_lshl_add_u64 v[140:141], v[144:145], 0, s[34:35]
	s_addc_u32 s69, s93, 0
	s_add_i32 s70, s71, s16
	global_load_lds_dwordx4 v[140:141], off
	v_lshl_add_u64 v[140:141], s[68:69], 0, v[0:1]
	s_mov_b32 m0, s70
	s_nop 0
	global_load_lds_dwordx4 v[140:141], off
	v_lshl_add_u64 v[140:141], s[68:69], 0, v[130:131]
	s_add_i32 m0, s70, 0x2000
	s_nop 0
	global_load_lds_dwordx4 v[140:141], off
	v_lshl_add_u64 v[140:141], v[148:149], 0, s[34:35]
	s_mov_b32 m0, s23
	s_nop 0
	global_load_lds_dwordx4 v[140:141], off
	v_lshl_add_u64 v[140:141], v[206:207], 0, s[34:35]
	s_mov_b32 m0, s29
	s_nop 0
	global_load_lds_dwordx4 v[140:141], off
	s_waitcnt vmcnt(8)
	s_waitcnt lgkmcnt(0)
	s_barrier
	s_waitcnt lgkmcnt(0)
	v_mfma_f32_16x16x32_bf16 v[62:65], v[154:157], v[186:189], v[62:65]
	v_mfma_f32_16x16x32_bf16 v[58:61], v[162:165], v[186:189], v[58:61]
	v_mfma_f32_16x16x32_bf16 v[50:53], v[154:157], v[194:197], v[50:53]
	v_mfma_f32_16x16x32_bf16 v[42:45], v[162:165], v[194:197], v[42:45]
	v_mfma_f32_16x16x32_bf16 v[34:37], v[154:157], v[202:205], v[34:37]
	v_mfma_f32_16x16x32_bf16 v[26:29], v[162:165], v[202:205], v[26:29]
	v_mfma_f32_16x16x32_bf16 v[18:21], v[154:157], v[214:217], v[18:21]
	v_mfma_f32_16x16x32_bf16 v[10:13], v[162:165], v[214:217], v[10:13]
	v_mfma_f32_16x16x32_bf16 v[54:57], v[170:173], v[186:189], v[54:57]
	v_mfma_f32_16x16x32_bf16 v[46:49], v[178:181], v[186:189], v[46:49]
	v_mfma_f32_16x16x32_bf16 v[38:41], v[170:173], v[194:197], v[38:41]
	v_mfma_f32_16x16x32_bf16 v[30:33], v[178:181], v[194:197], v[30:33]
	v_mfma_f32_16x16x32_bf16 v[22:25], v[170:173], v[202:205], v[22:25]
	v_mfma_f32_16x16x32_bf16 v[14:17], v[178:181], v[202:205], v[14:17]
	v_mfma_f32_16x16x32_bf16 v[6:9], v[170:173], v[214:217], v[6:9]
	v_mfma_f32_16x16x32_bf16 v[2:5], v[178:181], v[214:217], v[2:5]
	v_mfma_f32_16x16x32_bf16 v[62:65], v[158:161], v[190:193], v[62:65]
	v_mfma_f32_16x16x32_bf16 v[58:61], v[166:169], v[190:193], v[58:61]
	v_mfma_f32_16x16x32_bf16 v[50:53], v[158:161], v[198:201], v[50:53]
	v_mfma_f32_16x16x32_bf16 v[42:45], v[166:169], v[198:201], v[42:45]
	v_mfma_f32_16x16x32_bf16 v[34:37], v[158:161], v[210:213], v[34:37]
	v_mfma_f32_16x16x32_bf16 v[26:29], v[166:169], v[210:213], v[26:29]
	v_mfma_f32_16x16x32_bf16 v[18:21], v[158:161], v[218:221], v[18:21]
	v_mfma_f32_16x16x32_bf16 v[10:13], v[166:169], v[218:221], v[10:13]
	v_mfma_f32_16x16x32_bf16 v[54:57], v[174:177], v[190:193], v[54:57]
	v_mfma_f32_16x16x32_bf16 v[46:49], v[182:185], v[190:193], v[46:49]
	v_mfma_f32_16x16x32_bf16 v[38:41], v[174:177], v[198:201], v[38:41]
	v_mfma_f32_16x16x32_bf16 v[30:33], v[182:185], v[198:201], v[30:33]
	v_mfma_f32_16x16x32_bf16 v[22:25], v[174:177], v[210:213], v[22:25]
	v_mfma_f32_16x16x32_bf16 v[14:17], v[182:185], v[210:213], v[14:17]
	v_mfma_f32_16x16x32_bf16 v[6:9], v[174:177], v[218:221], v[6:9]
	v_mfma_f32_16x16x32_bf16 v[2:5], v[182:185], v[218:221], v[2:5]
	s_barrier
	s_add_i32 s97, s97, 2
	s_add_u32 s90, s90, 0x100
	s_addc_u32 s91, s91, 0
	s_add_u32 s89, s89, 0x100
	s_addc_u32 s96, s96, 0
	s_cmp_gt_u32 s97, 13
	s_cbranch_scc0 .LBB0_75
	s_and_b64 vcc, exec, s[46:47]
	s_cbranch_vccz .LBB0_78
	s_barrier

.LBB0_188:
	s_add_i32 vcc_lo, s92, 2
	s_add_u32 s68, s40, 0x80
	s_addc_u32 s69, s41, 0
	s_add_i32 s70, 0, 0x10000
	s_cmp_eq_u32 s96, s92
	s_cselect_b32 s93, s89, s69
	s_cselect_b32 s92, s88, s68
	s_cselect_b32 s69, s91, s95
	s_cselect_b32 s68, s90, s94
	s_add_i32 s71, 0, 0x14000
	v_add_u32_e32 v126, s70, v162
	v_add_u32_e32 v172, s71, v162
	ds_read_b128 v[106:109], v126
	ds_read_b128 v[110:113], v126 offset:1024
	ds_read_b128 v[122:125], v126 offset:2048
	ds_read_b128 v[126:129], v126 offset:3072
	ds_read_b128 v[156:159], v172
	ds_read_b128 v[164:167], v172 offset:1024
	ds_read_b128 v[168:171], v172 offset:2048
	ds_read_b128 v[172:175], v172 offset:3072
	v_lshl_add_u64 v[210:211], s[40:41], 0, v[152:153]
	s_add_i32 m0, s19, 0xc000
	ds_read_b128 v[176:179], v163
	ds_read_b128 v[180:183], v163 offset:1024
	ds_read_b128 v[184:187], v163 offset:2048
	ds_read_b128 v[188:191], v163 offset:3072
	ds_read_b128 v[192:195], v163 offset:4096
	ds_read_b128 v[196:199], v163 offset:5120
	ds_read_b128 v[200:203], v163 offset:6144
	ds_read_b128 v[204:207], v163 offset:7168
	global_load_lds_dwordx4 v[210:211], off
	v_lshl_add_u64 v[210:211], s[40:41], 0, v[154:155]
	s_add_i32 m0, s19, 0xe000
	s_nop 0
	global_load_lds_dwordx4 v[210:211], off
	s_waitcnt vmcnt(8)
	s_waitcnt lgkmcnt(0)
	s_barrier
	s_waitcnt lgkmcnt(0)
	v_mfma_f32_16x16x32_bf16 v[142:145], v[106:109], v[176:179], v[142:145]
	v_mfma_f32_16x16x32_bf16 v[138:141], v[122:125], v[176:179], v[138:141]
	v_mfma_f32_16x16x32_bf16 v[118:121], v[106:109], v[184:187], v[118:121]
	v_mfma_f32_16x16x32_bf16 v[114:117], v[122:125], v[184:187], v[114:117]
	v_mfma_f32_16x16x32_bf16 v[94:97], v[106:109], v[192:195], v[94:97]
	v_mfma_f32_16x16x32_bf16 v[90:93], v[122:125], v[192:195], v[90:93]
	v_mfma_f32_16x16x32_bf16 v[78:81], v[106:109], v[200:203], v[78:81]
	v_mfma_f32_16x16x32_bf16 v[74:77], v[122:125], v[200:203], v[74:77]
	v_mfma_f32_16x16x32_bf16 v[134:137], v[156:159], v[176:179], v[134:137]
	v_mfma_f32_16x16x32_bf16 v[130:133], v[168:171], v[176:179], v[130:133]
	v_mfma_f32_16x16x32_bf16 v[102:105], v[156:159], v[184:187], v[102:105]
	v_mfma_f32_16x16x32_bf16 v[98:101], v[168:171], v[184:187], v[98:101]
	v_mfma_f32_16x16x32_bf16 v[86:89], v[156:159], v[192:195], v[86:89]
	v_mfma_f32_16x16x32_bf16 v[82:85], v[168:171], v[192:195], v[82:85]
	v_mfma_f32_16x16x32_bf16 v[70:73], v[156:159], v[200:203], v[70:73]
	v_mfma_f32_16x16x32_bf16 v[66:69], v[168:171], v[200:203], v[66:69]
	v_mfma_f32_16x16x32_bf16 v[142:145], v[110:113], v[180:183], v[142:145]
	v_mfma_f32_16x16x32_bf16 v[138:141], v[126:129], v[180:183], v[138:141]
	v_mfma_f32_16x16x32_bf16 v[118:121], v[110:113], v[188:191], v[118:121]
	v_mfma_f32_16x16x32_bf16 v[114:117], v[126:129], v[188:191], v[114:117]
	v_mfma_f32_16x16x32_bf16 v[94:97], v[110:113], v[196:199], v[94:97]
	v_mfma_f32_16x16x32_bf16 v[90:93], v[126:129], v[196:199], v[90:93]
	v_mfma_f32_16x16x32_bf16 v[78:81], v[110:113], v[204:207], v[78:81]
	v_mfma_f32_16x16x32_bf16 v[74:77], v[126:129], v[204:207], v[74:77]
	v_mfma_f32_16x16x32_bf16 v[134:137], v[164:167], v[180:183], v[134:137]
	v_mfma_f32_16x16x32_bf16 v[130:133], v[172:175], v[180:183], v[130:133]
	v_mfma_f32_16x16x32_bf16 v[102:105], v[164:167], v[188:191], v[102:105]
	v_mfma_f32_16x16x32_bf16 v[98:101], v[172:175], v[188:191], v[98:101]
	v_mfma_f32_16x16x32_bf16 v[86:89], v[164:167], v[196:199], v[86:89]
	v_mfma_f32_16x16x32_bf16 v[82:85], v[172:175], v[196:199], v[82:85]
	v_mfma_f32_16x16x32_bf16 v[70:73], v[164:167], v[204:207], v[70:73]
	v_mfma_f32_16x16x32_bf16 v[66:69], v[172:175], v[204:207], v[66:69]
	s_barrier
	s_add_i32 s70, s70, s18
	v_lshl_add_u64 v[210:211], s[68:69], 0, v[0:1]
	s_mov_b32 m0, s70
	ds_read_b128 v[176:179], v163 offset:16384
	ds_read_b128 v[180:183], v163 offset:17408
	ds_read_b128 v[184:187], v163 offset:18432
	ds_read_b128 v[188:191], v163 offset:19456
	ds_read_b128 v[192:195], v163 offset:20480
	ds_read_b128 v[196:199], v163 offset:21504
	ds_read_b128 v[200:203], v163 offset:22528
	ds_read_b128 v[204:207], v163 offset:23552
	global_load_lds_dwordx4 v[210:211], off
	s_add_i32 m0, s70, 0x2000
	v_lshl_add_u64 v[212:213], s[68:69], 0, v[150:151]
	s_add_u32 s68, s68, s26
	s_addc_u32 s69, s69, 0
	s_add_i32 s70, s71, s18
	global_load_lds_dwordx4 v[212:213], off
	v_lshl_add_u64 v[214:215], s[68:69], 0, v[0:1]
	s_mov_b32 m0, s70
	v_lshl_add_u64 v[216:217], s[68:69], 0, v[150:151]
	global_load_lds_dwordx4 v[214:215], off
	s_add_i32 m0, s70, 0x2000
	v_lshl_add_u64 v[218:219], s[92:93], 0, v[146:147]
	global_load_lds_dwordx4 v[216:217], off
	s_mov_b32 m0, s19
	v_lshl_add_u64 v[220:221], s[92:93], 0, v[148:149]
	global_load_lds_dwordx4 v[218:219], off
	s_mov_b32 m0, s20
	s_nop 0
	global_load_lds_dwordx4 v[220:221], off
	s_waitcnt vmcnt(8)
	s_waitcnt lgkmcnt(0)
	s_barrier
	s_waitcnt lgkmcnt(0)
	v_mfma_f32_16x16x32_bf16 v[62:65], v[106:109], v[176:179], v[62:65]
	v_mfma_f32_16x16x32_bf16 v[58:61], v[122:125], v[176:179], v[58:61]
	v_mfma_f32_16x16x32_bf16 v[46:49], v[106:109], v[184:187], v[46:49]
	v_mfma_f32_16x16x32_bf16 v[42:45], v[122:125], v[184:187], v[42:45]
	v_mfma_f32_16x16x32_bf16 v[30:33], v[106:109], v[192:195], v[30:33]
	v_mfma_f32_16x16x32_bf16 v[26:29], v[122:125], v[192:195], v[26:29]
	v_mfma_f32_16x16x32_bf16 v[14:17], v[106:109], v[200:203], v[14:17]
	v_mfma_f32_16x16x32_bf16 v[10:13], v[122:125], v[200:203], v[10:13]
	v_mfma_f32_16x16x32_bf16 v[54:57], v[156:159], v[176:179], v[54:57]
	v_mfma_f32_16x16x32_bf16 v[50:53], v[168:171], v[176:179], v[50:53]
	v_mfma_f32_16x16x32_bf16 v[38:41], v[156:159], v[184:187], v[38:41]
	v_mfma_f32_16x16x32_bf16 v[34:37], v[168:171], v[184:187], v[34:37]
	v_mfma_f32_16x16x32_bf16 v[22:25], v[156:159], v[192:195], v[22:25]
	v_mfma_f32_16x16x32_bf16 v[18:21], v[168:171], v[192:195], v[18:21]
	v_mfma_f32_16x16x32_bf16 v[6:9], v[156:159], v[200:203], v[6:9]
	v_mfma_f32_16x16x32_bf16 v[2:5], v[168:171], v[200:203], v[2:5]
	v_mfma_f32_16x16x32_bf16 v[62:65], v[110:113], v[180:183], v[62:65]
	v_mfma_f32_16x16x32_bf16 v[58:61], v[126:129], v[180:183], v[58:61]
	v_mfma_f32_16x16x32_bf16 v[46:49], v[110:113], v[188:191], v[46:49]
	v_mfma_f32_16x16x32_bf16 v[42:45], v[126:129], v[188:191], v[42:45]
	v_mfma_f32_16x16x32_bf16 v[30:33], v[110:113], v[196:199], v[30:33]
	v_mfma_f32_16x16x32_bf16 v[26:29], v[126:129], v[196:199], v[26:29]
	v_mfma_f32_16x16x32_bf16 v[14:17], v[110:113], v[204:207], v[14:17]
	v_mfma_f32_16x16x32_bf16 v[10:13], v[126:129], v[204:207], v[10:13]
	v_mfma_f32_16x16x32_bf16 v[54:57], v[164:167], v[180:183], v[54:57]
	v_mfma_f32_16x16x32_bf16 v[50:53], v[172:175], v[180:183], v[50:53]
	v_mfma_f32_16x16x32_bf16 v[38:41], v[164:167], v[188:191], v[38:41]
	v_mfma_f32_16x16x32_bf16 v[34:37], v[172:175], v[188:191], v[34:37]
	v_mfma_f32_16x16x32_bf16 v[22:25], v[164:167], v[196:199], v[22:25]
	v_mfma_f32_16x16x32_bf16 v[18:21], v[172:175], v[196:199], v[18:21]
	v_mfma_f32_16x16x32_bf16 v[6:9], v[164:167], v[204:207], v[6:9]
	v_mfma_f32_16x16x32_bf16 v[2:5], v[172:175], v[204:207], v[2:5]
	s_barrier
	s_add_i32 s70, 0, 0x18000
	s_add_i32 s71, 0, 0x1c000
	v_add_u32_e32 v126, s70, v162
	v_add_u32_e32 v172, s71, v162
	ds_read_b128 v[106:109], v126
	ds_read_b128 v[110:113], v126 offset:1024
	ds_read_b128 v[122:125], v126 offset:2048
	ds_read_b128 v[126:129], v126 offset:3072
	ds_read_b128 v[156:159], v172
	ds_read_b128 v[164:167], v172 offset:1024
	ds_read_b128 v[168:171], v172 offset:2048
	ds_read_b128 v[172:175], v172 offset:3072
	s_add_u32 s68, s92, s26
	s_addc_u32 s69, s93, 0
	s_mov_b32 m0, s21
	v_lshl_add_u64 v[222:223], s[68:69], 0, v[146:147]
	ds_read_b128 v[176:179], v163 offset:32768
	ds_read_b128 v[180:183], v163 offset:33792
	ds_read_b128 v[184:187], v163 offset:34816
	ds_read_b128 v[188:191], v163 offset:35840
	ds_read_b128 v[192:195], v163 offset:36864
	ds_read_b128 v[196:199], v163 offset:37888
	ds_read_b128 v[200:203], v163 offset:38912
	ds_read_b128 v[204:207], v163 offset:39936
	global_load_lds_dwordx4 v[222:223], off
	v_lshl_add_u64 v[222:223], s[68:69], 0, v[148:149]
	s_mov_b32 m0, s22
	s_nop 0
	global_load_lds_dwordx4 v[222:223], off
	s_waitcnt vmcnt(8)
	s_waitcnt lgkmcnt(0)
	s_barrier
	s_waitcnt lgkmcnt(0)
	v_mfma_f32_16x16x32_bf16 v[142:145], v[106:109], v[176:179], v[142:145]
	v_mfma_f32_16x16x32_bf16 v[138:141], v[122:125], v[176:179], v[138:141]
	v_mfma_f32_16x16x32_bf16 v[118:121], v[106:109], v[184:187], v[118:121]
	v_mfma_f32_16x16x32_bf16 v[114:117], v[122:125], v[184:187], v[114:117]
	v_mfma_f32_16x16x32_bf16 v[94:97], v[106:109], v[192:195], v[94:97]
	v_mfma_f32_16x16x32_bf16 v[90:93], v[122:125], v[192:195], v[90:93]
	v_mfma_f32_16x16x32_bf16 v[78:81], v[106:109], v[200:203], v[78:81]
	v_mfma_f32_16x16x32_bf16 v[74:77], v[122:125], v[200:203], v[74:77]
	v_mfma_f32_16x16x32_bf16 v[134:137], v[156:159], v[176:179], v[134:137]
	v_mfma_f32_16x16x32_bf16 v[130:133], v[168:171], v[176:179], v[130:133]
	v_mfma_f32_16x16x32_bf16 v[102:105], v[156:159], v[184:187], v[102:105]
	v_mfma_f32_16x16x32_bf16 v[98:101], v[168:171], v[184:187], v[98:101]
	v_mfma_f32_16x16x32_bf16 v[86:89], v[156:159], v[192:195], v[86:89]
	v_mfma_f32_16x16x32_bf16 v[82:85], v[168:171], v[192:195], v[82:85]
	v_mfma_f32_16x16x32_bf16 v[70:73], v[156:159], v[200:203], v[70:73]
	v_mfma_f32_16x16x32_bf16 v[66:69], v[168:171], v[200:203], v[66:69]
	v_mfma_f32_16x16x32_bf16 v[142:145], v[110:113], v[180:183], v[142:145]
	v_mfma_f32_16x16x32_bf16 v[138:141], v[126:129], v[180:183], v[138:141]
	v_mfma_f32_16x16x32_bf16 v[118:121], v[110:113], v[188:191], v[118:121]
	v_mfma_f32_16x16x32_bf16 v[114:117], v[126:129], v[188:191], v[114:117]
	v_mfma_f32_16x16x32_bf16 v[94:97], v[110:113], v[196:199], v[94:97]
	v_mfma_f32_16x16x32_bf16 v[90:93], v[126:129], v[196:199], v[90:93]
	v_mfma_f32_16x16x32_bf16 v[78:81], v[110:113], v[204:207], v[78:81]
	v_mfma_f32_16x16x32_bf16 v[74:77], v[126:129], v[204:207], v[74:77]
	v_mfma_f32_16x16x32_bf16 v[134:137], v[164:167], v[180:183], v[134:137]
	v_mfma_f32_16x16x32_bf16 v[130:133], v[172:175], v[180:183], v[130:133]
	v_mfma_f32_16x16x32_bf16 v[102:105], v[164:167], v[188:191], v[102:105]
	v_mfma_f32_16x16x32_bf16 v[98:101], v[172:175], v[188:191], v[98:101]
	v_mfma_f32_16x16x32_bf16 v[86:89], v[164:167], v[196:199], v[86:89]
	v_mfma_f32_16x16x32_bf16 v[82:85], v[172:175], v[196:199], v[82:85]
	v_mfma_f32_16x16x32_bf16 v[70:73], v[164:167], v[204:207], v[70:73]
	v_mfma_f32_16x16x32_bf16 v[66:69], v[172:175], v[204:207], v[66:69]
	s_barrier
	s_add_i32 s68, s70, s18
	v_lshl_add_u64 v[210:211], v[210:211], 0, s[34:35]
	s_mov_b32 m0, s68
	ds_read_b128 v[176:179], v163 offset:49152
	ds_read_b128 v[180:183], v163 offset:50176
	ds_read_b128 v[184:187], v163 offset:51200
	ds_read_b128 v[188:191], v163 offset:52224
	ds_read_b128 v[192:195], v163 offset:53248
	ds_read_b128 v[196:199], v163 offset:54272
	ds_read_b128 v[200:203], v163 offset:55296
	ds_read_b128 v[204:207], v163 offset:56320
	global_load_lds_dwordx4 v[210:211], off
	v_lshl_add_u64 v[210:211], v[212:213], 0, s[34:35]
	s_add_i32 m0, s68, 0x2000
	s_add_i32 s68, s71, s18
	global_load_lds_dwordx4 v[210:211], off
	v_lshl_add_u64 v[210:211], v[214:215], 0, s[34:35]
	s_mov_b32 m0, s68
	s_nop 0
	global_load_lds_dwordx4 v[210:211], off
	v_lshl_add_u64 v[210:211], v[216:217], 0, s[34:35]
	s_add_i32 m0, s68, 0x2000
	s_nop 0
	global_load_lds_dwordx4 v[210:211], off
	v_lshl_add_u64 v[210:211], v[218:219], 0, s[34:35]
	s_mov_b32 m0, s81
	s_nop 0
	global_load_lds_dwordx4 v[210:211], off
	v_lshl_add_u64 v[210:211], v[220:221], 0, s[34:35]
	s_mov_b32 m0, s83
	s_nop 0
	global_load_lds_dwordx4 v[210:211], off
	s_waitcnt vmcnt(8)
	s_waitcnt lgkmcnt(0)
	s_barrier
	s_waitcnt lgkmcnt(0)
	v_mfma_f32_16x16x32_bf16 v[62:65], v[106:109], v[176:179], v[62:65]
	v_mfma_f32_16x16x32_bf16 v[58:61], v[122:125], v[176:179], v[58:61]
	v_mfma_f32_16x16x32_bf16 v[46:49], v[106:109], v[184:187], v[46:49]
	v_mfma_f32_16x16x32_bf16 v[42:45], v[122:125], v[184:187], v[42:45]
	v_mfma_f32_16x16x32_bf16 v[30:33], v[106:109], v[192:195], v[30:33]
	v_mfma_f32_16x16x32_bf16 v[26:29], v[122:125], v[192:195], v[26:29]
	v_mfma_f32_16x16x32_bf16 v[14:17], v[106:109], v[200:203], v[14:17]
	v_mfma_f32_16x16x32_bf16 v[10:13], v[122:125], v[200:203], v[10:13]
	v_mfma_f32_16x16x32_bf16 v[54:57], v[156:159], v[176:179], v[54:57]
	v_mfma_f32_16x16x32_bf16 v[50:53], v[168:171], v[176:179], v[50:53]
	v_mfma_f32_16x16x32_bf16 v[38:41], v[156:159], v[184:187], v[38:41]
	v_mfma_f32_16x16x32_bf16 v[34:37], v[168:171], v[184:187], v[34:37]
	v_mfma_f32_16x16x32_bf16 v[22:25], v[156:159], v[192:195], v[22:25]
	v_mfma_f32_16x16x32_bf16 v[18:21], v[168:171], v[192:195], v[18:21]
	v_mfma_f32_16x16x32_bf16 v[6:9], v[156:159], v[200:203], v[6:9]
	v_mfma_f32_16x16x32_bf16 v[2:5], v[168:171], v[200:203], v[2:5]
	v_mfma_f32_16x16x32_bf16 v[62:65], v[110:113], v[180:183], v[62:65]
	v_mfma_f32_16x16x32_bf16 v[58:61], v[126:129], v[180:183], v[58:61]
	v_mfma_f32_16x16x32_bf16 v[46:49], v[110:113], v[188:191], v[46:49]
	v_mfma_f32_16x16x32_bf16 v[42:45], v[126:129], v[188:191], v[42:45]
	v_mfma_f32_16x16x32_bf16 v[30:33], v[110:113], v[196:199], v[30:33]
	v_mfma_f32_16x16x32_bf16 v[26:29], v[126:129], v[196:199], v[26:29]
	v_mfma_f32_16x16x32_bf16 v[14:17], v[110:113], v[204:207], v[14:17]
	v_mfma_f32_16x16x32_bf16 v[10:13], v[126:129], v[204:207], v[10:13]
	v_mfma_f32_16x16x32_bf16 v[54:57], v[164:167], v[180:183], v[54:57]
	v_mfma_f32_16x16x32_bf16 v[50:53], v[172:175], v[180:183], v[50:53]
	v_mfma_f32_16x16x32_bf16 v[38:41], v[164:167], v[188:191], v[38:41]
	v_mfma_f32_16x16x32_bf16 v[34:37], v[172:175], v[188:191], v[34:37]
	v_mfma_f32_16x16x32_bf16 v[22:25], v[164:167], v[196:199], v[22:25]
	v_mfma_f32_16x16x32_bf16 v[18:21], v[172:175], v[196:199], v[18:21]
	v_mfma_f32_16x16x32_bf16 v[6:9], v[164:167], v[204:207], v[6:9]
	v_mfma_f32_16x16x32_bf16 v[2:5], v[172:175], v[204:207], v[2:5]
	s_barrier
	s_add_u32 s40, s40, 0x100
	s_addc_u32 s41, s41, 0
	s_add_u32 s94, s94, 0x100
	s_addc_u32 s95, s95, 0
	s_cmp_ge_u32 vcc_lo, s29
	s_mov_b32 s92, vcc_lo
	s_cbranch_scc0 .LBB0_188
	s_and_b64 vcc, exec, s[78:79]
	s_cbranch_vccz .LBB0_191
	s_barrier

.LBB0_243:
	s_add_u32 s70, s42, 0xfffc0080
	s_addc_u32 s71, s43, -1
	s_add_i32 s72, 0, 0x10000
	s_cmp_eq_u32 s95, 12
	s_cselect_b32 vcc_hi, s2, s71
	s_cselect_b32 vcc_lo, s6, s70
	v_add_u32_e32 v0, s72, v181
	s_cselect_b32 s93, s41, s89
	s_cselect_b32 s92, s48, s77
	s_add_i32 s73, 0, 0x14000
	ds_read_b128 v[14:17], v0
	ds_read_b128 v[22:25], v0 offset:1024
	ds_read_b128 v[26:29], v0 offset:2048
	ds_read_b128 v[74:77], v0 offset:3072
	v_add_u32_e32 v0, s73, v181
	ds_read_b128 v[78:81], v0
	ds_read_b128 v[82:85], v0 offset:1024
	ds_read_b128 v[154:157], v0 offset:2048
	ds_read_b128 v[158:161], v0 offset:3072
	v_lshl_add_u64 v[174:175], s[42:43], 0, v[170:171]
	s_add_i32 m0, s81, 0xc000
	ds_read_b128 v[182:185], v189
	ds_read_b128 v[190:193], v189 offset:1024
	ds_read_b128 v[194:197], v189 offset:2048
	ds_read_b128 v[198:201], v189 offset:3072
	ds_read_b128 v[202:205], v189 offset:4096
	ds_read_b128 v[210:213], v189 offset:5120
	ds_read_b128 v[214:217], v189 offset:6144
	ds_read_b128 v[218:221], v189 offset:7168
	global_load_lds_dwordx4 v[174:175], off
	v_lshl_add_u64 v[174:175], s[42:43], 0, v[172:173]
	s_add_i32 m0, s81, 0xe000
	s_nop 0
	global_load_lds_dwordx4 v[174:175], off
	s_waitcnt vmcnt(8)
	s_waitcnt lgkmcnt(0)
	s_barrier
	s_waitcnt lgkmcnt(0)
	v_mfma_f32_16x16x32_bf16 v[150:153], v[14:17], v[182:185], v[150:153]
	v_mfma_f32_16x16x32_bf16 v[58:61], v[26:29], v[182:185], v[58:61]
	v_mfma_f32_16x16x32_bf16 v[126:129], v[14:17], v[194:197], v[126:129]
	v_mfma_f32_16x16x32_bf16 v[122:125], v[26:29], v[194:197], v[122:125]
	v_mfma_f32_16x16x32_bf16 v[118:121], v[14:17], v[202:205], v[118:121]
	v_mfma_f32_16x16x32_bf16 v[114:117], v[26:29], v[202:205], v[114:117]
	v_mfma_f32_16x16x32_bf16 v[134:137], v[14:17], v[214:217], v[134:137]
	v_mfma_f32_16x16x32_bf16 v[130:133], v[26:29], v[214:217], v[130:133]
	v_mfma_f32_16x16x32_bf16 v[142:145], v[78:81], v[182:185], v[142:145]
	v_mfma_f32_16x16x32_bf16 v[138:141], v[154:157], v[182:185], v[138:141]
	v_mfma_f32_16x16x32_bf16 v[110:113], v[78:81], v[194:197], v[110:113]
	v_mfma_f32_16x16x32_bf16 v[106:109], v[154:157], v[194:197], v[106:109]
	v_mfma_f32_16x16x32_bf16 v[102:105], v[78:81], v[202:205], v[102:105]
	v_mfma_f32_16x16x32_bf16 v[98:101], v[154:157], v[202:205], v[98:101]
	v_mfma_f32_16x16x32_bf16 v[94:97], v[78:81], v[214:217], v[94:97]
	v_mfma_f32_16x16x32_bf16 v[90:93], v[154:157], v[214:217], v[90:93]
	v_mfma_f32_16x16x32_bf16 v[150:153], v[22:25], v[190:193], v[150:153]
	v_mfma_f32_16x16x32_bf16 v[58:61], v[74:77], v[190:193], v[58:61]
	v_mfma_f32_16x16x32_bf16 v[126:129], v[22:25], v[198:201], v[126:129]
	v_mfma_f32_16x16x32_bf16 v[122:125], v[74:77], v[198:201], v[122:125]
	v_mfma_f32_16x16x32_bf16 v[118:121], v[22:25], v[210:213], v[118:121]
	v_mfma_f32_16x16x32_bf16 v[114:117], v[74:77], v[210:213], v[114:117]
	v_mfma_f32_16x16x32_bf16 v[134:137], v[22:25], v[218:221], v[134:137]
	v_mfma_f32_16x16x32_bf16 v[130:133], v[74:77], v[218:221], v[130:133]
	v_mfma_f32_16x16x32_bf16 v[142:145], v[82:85], v[190:193], v[142:145]
	v_mfma_f32_16x16x32_bf16 v[138:141], v[158:161], v[190:193], v[138:141]
	v_mfma_f32_16x16x32_bf16 v[110:113], v[82:85], v[198:201], v[110:113]
	v_mfma_f32_16x16x32_bf16 v[106:109], v[158:161], v[198:201], v[106:109]
	v_mfma_f32_16x16x32_bf16 v[102:105], v[82:85], v[210:213], v[102:105]
	v_mfma_f32_16x16x32_bf16 v[98:101], v[158:161], v[210:213], v[98:101]
	v_mfma_f32_16x16x32_bf16 v[94:97], v[82:85], v[218:221], v[94:97]
	v_mfma_f32_16x16x32_bf16 v[90:93], v[158:161], v[218:221], v[90:93]
	s_barrier
	s_add_i32 s70, s72, s29
	v_lshl_add_u64 v[174:175], s[92:93], 0, v[164:165]
	s_mov_b32 m0, s70
	ds_read_b128 v[182:185], v189 offset:16384
	ds_read_b128 v[190:193], v189 offset:17408
	ds_read_b128 v[194:197], v189 offset:18432
	ds_read_b128 v[198:201], v189 offset:19456
	ds_read_b128 v[202:205], v189 offset:20480
	ds_read_b128 v[210:213], v189 offset:21504
	ds_read_b128 v[214:217], v189 offset:22528
	ds_read_b128 v[218:221], v189 offset:23552
	global_load_lds_dwordx4 v[174:175], off
	s_add_i32 m0, s70, 0x2000
	s_add_u32 s70, s92, 0x40000
	v_lshl_add_u64 v[186:187], s[92:93], 0, v[168:169]
	s_addc_u32 s71, s93, 0
	s_add_i32 s72, s73, s29
	global_load_lds_dwordx4 v[186:187], off
	v_lshl_add_u64 v[206:207], s[70:71], 0, v[164:165]
	s_mov_b32 m0, s72
	v_lshl_add_u64 v[226:227], vcc, 0, v[166:167]
	global_load_lds_dwordx4 v[206:207], off
	v_lshl_add_u64 v[206:207], s[70:71], 0, v[168:169]
	s_add_i32 m0, s72, 0x2000
	s_nop 0
	global_load_lds_dwordx4 v[206:207], off
	v_lshl_add_u64 v[206:207], vcc, 0, v[162:163]
	s_mov_b32 m0, s81
	s_nop 0
	global_load_lds_dwordx4 v[206:207], off
	s_mov_b32 m0, s83
	s_nop 0
	global_load_lds_dwordx4 v[226:227], off
	s_waitcnt vmcnt(8)
	s_waitcnt lgkmcnt(0)
	s_barrier
	s_waitcnt lgkmcnt(0)
	v_mfma_f32_16x16x32_bf16 v[70:73], v[14:17], v[182:185], v[70:73]
	v_mfma_f32_16x16x32_bf16 v[66:69], v[26:29], v[182:185], v[66:69]
	v_mfma_f32_16x16x32_bf16 v[62:65], v[14:17], v[194:197], v[62:65]
	v_mfma_f32_16x16x32_bf16 v[54:57], v[26:29], v[194:197], v[54:57]
	v_mfma_f32_16x16x32_bf16 v[42:45], v[14:17], v[202:205], v[42:45]
	v_mfma_f32_16x16x32_bf16 v[38:41], v[26:29], v[202:205], v[38:41]
	v_mfma_f32_16x16x32_bf16 v[14:17], v[14:17], v[214:217], v[86:89]
	v_mfma_f32_16x16x32_bf16 v[46:49], v[154:157], v[182:185], v[46:49]
	v_mfma_f32_16x16x32_bf16 v[34:37], v[78:81], v[194:197], v[34:37]
	v_mfma_f32_16x16x32_bf16 v[30:33], v[154:157], v[194:197], v[30:33]
	v_mfma_f32_16x16x32_bf16 v[18:21], v[78:81], v[202:205], v[18:21]
	v_mfma_f32_16x16x32_bf16 v[10:13], v[154:157], v[202:205], v[10:13]
	v_mfma_f32_16x16x32_bf16 v[6:9], v[78:81], v[214:217], v[6:9]
	v_mfma_f32_16x16x32_bf16 v[2:5], v[154:157], v[214:217], v[2:5]
	v_mfma_f32_16x16x32_bf16 v[70:73], v[22:25], v[190:193], v[70:73]
	v_mfma_f32_16x16x32_bf16 v[66:69], v[74:77], v[190:193], v[66:69]
	v_mfma_f32_16x16x32_bf16 v[62:65], v[22:25], v[198:201], v[62:65]
	v_mfma_f32_16x16x32_bf16 v[54:57], v[74:77], v[198:201], v[54:57]
	v_mfma_f32_16x16x32_bf16 v[42:45], v[22:25], v[210:213], v[42:45]
	v_mfma_f32_16x16x32_bf16 v[38:41], v[74:77], v[210:213], v[38:41]
	v_mfma_f32_16x16x32_bf16 v[14:17], v[22:25], v[218:221], v[14:17]
	v_mfma_f32_16x16x32_bf16 v[22:25], v[26:29], v[214:217], v[146:149]
	v_mfma_f32_16x16x32_bf16 v[26:29], v[78:81], v[182:185], v[50:53]
	v_mfma_f32_16x16x32_bf16 v[46:49], v[158:161], v[190:193], v[46:49]
	v_mfma_f32_16x16x32_bf16 v[34:37], v[82:85], v[198:201], v[34:37]
	v_mfma_f32_16x16x32_bf16 v[30:33], v[158:161], v[198:201], v[30:33]
	v_mfma_f32_16x16x32_bf16 v[18:21], v[82:85], v[210:213], v[18:21]
	v_mfma_f32_16x16x32_bf16 v[10:13], v[158:161], v[210:213], v[10:13]
	v_mfma_f32_16x16x32_bf16 v[6:9], v[82:85], v[218:221], v[6:9]
	v_mfma_f32_16x16x32_bf16 v[2:5], v[158:161], v[218:221], v[2:5]
	v_mfma_f32_16x16x32_bf16 v[22:25], v[74:77], v[218:221], v[22:25]
	v_mfma_f32_16x16x32_bf16 v[26:29], v[82:85], v[190:193], v[26:29]
	s_barrier
	s_add_i32 s72, 0, 0x18000
	v_add_u32_e32 v0, s72, v181
	s_add_i32 s73, 0, 0x1c000
	ds_read_b128 v[50:53], v0
	ds_read_b128 v[74:77], v0 offset:1024
	ds_read_b128 v[78:81], v0 offset:2048
	ds_read_b128 v[82:85], v0 offset:3072
	v_add_u32_e32 v0, s73, v181
	ds_read_b128 v[154:157], v0
	ds_read_b128 v[158:161], v0 offset:1024
	ds_read_b128 v[182:185], v0 offset:2048
	ds_read_b128 v[190:193], v0 offset:3072
	s_add_u32 s70, vcc_lo, 0x40000
	s_addc_u32 s71, vcc_hi, 0
	s_mov_b32 m0, s16
	v_lshl_add_u64 v[222:223], s[70:71], 0, v[162:163]
	ds_read_b128 v[86:89], v189 offset:32768
	ds_read_b128 v[146:149], v189 offset:33792
	ds_read_b128 v[194:197], v189 offset:34816
	ds_read_b128 v[198:201], v189 offset:35840
	ds_read_b128 v[202:205], v189 offset:36864
	ds_read_b128 v[210:213], v189 offset:37888
	ds_read_b128 v[214:217], v189 offset:38912
	ds_read_b128 v[218:221], v189 offset:39936
	global_load_lds_dwordx4 v[222:223], off
	v_lshl_add_u64 v[222:223], s[70:71], 0, v[166:167]
	s_mov_b32 m0, s17
	s_nop 0
	global_load_lds_dwordx4 v[222:223], off
	s_waitcnt vmcnt(8)
	s_waitcnt lgkmcnt(0)
	s_barrier
	s_waitcnt lgkmcnt(0)
	v_mfma_f32_16x16x32_bf16 v[150:153], v[50:53], v[86:89], v[150:153]
	v_mfma_f32_16x16x32_bf16 v[58:61], v[78:81], v[86:89], v[58:61]
	v_mfma_f32_16x16x32_bf16 v[142:145], v[154:157], v[86:89], v[142:145]
	v_mfma_f32_16x16x32_bf16 v[86:89], v[182:185], v[86:89], v[138:141]
	v_mfma_f32_16x16x32_bf16 v[138:141], v[190:193], v[146:149], v[86:89]
	v_mfma_f32_16x16x32_bf16 v[86:89], v[154:157], v[194:197], v[110:113]
	v_mfma_f32_16x16x32_bf16 v[110:113], v[158:161], v[198:201], v[86:89]
	v_mfma_f32_16x16x32_bf16 v[86:89], v[182:185], v[194:197], v[106:109]
	v_mfma_f32_16x16x32_bf16 v[106:109], v[190:193], v[198:201], v[86:89]
	v_mfma_f32_16x16x32_bf16 v[86:89], v[154:157], v[202:205], v[102:105]
	v_mfma_f32_16x16x32_bf16 v[102:105], v[158:161], v[210:213], v[86:89]
	v_mfma_f32_16x16x32_bf16 v[86:89], v[182:185], v[202:205], v[98:101]
	v_mfma_f32_16x16x32_bf16 v[98:101], v[190:193], v[210:213], v[86:89]
	v_mfma_f32_16x16x32_bf16 v[86:89], v[154:157], v[214:217], v[94:97]
	v_mfma_f32_16x16x32_bf16 v[126:129], v[50:53], v[194:197], v[126:129]
	v_mfma_f32_16x16x32_bf16 v[122:125], v[78:81], v[194:197], v[122:125]
	v_mfma_f32_16x16x32_bf16 v[118:121], v[50:53], v[202:205], v[118:121]
	v_mfma_f32_16x16x32_bf16 v[114:117], v[78:81], v[202:205], v[114:117]
	v_mfma_f32_16x16x32_bf16 v[134:137], v[50:53], v[214:217], v[134:137]
	v_mfma_f32_16x16x32_bf16 v[130:133], v[78:81], v[214:217], v[130:133]
	v_mfma_f32_16x16x32_bf16 v[94:97], v[158:161], v[218:221], v[86:89]
	v_mfma_f32_16x16x32_bf16 v[86:89], v[182:185], v[214:217], v[90:93]
	v_mfma_f32_16x16x32_bf16 v[150:153], v[74:77], v[146:149], v[150:153]
	v_mfma_f32_16x16x32_bf16 v[58:61], v[82:85], v[146:149], v[58:61]
	v_mfma_f32_16x16x32_bf16 v[126:129], v[74:77], v[198:201], v[126:129]
	v_mfma_f32_16x16x32_bf16 v[122:125], v[82:85], v[198:201], v[122:125]
	v_mfma_f32_16x16x32_bf16 v[118:121], v[74:77], v[210:213], v[118:121]
	v_mfma_f32_16x16x32_bf16 v[114:117], v[82:85], v[210:213], v[114:117]
	v_mfma_f32_16x16x32_bf16 v[134:137], v[74:77], v[218:221], v[134:137]
	v_mfma_f32_16x16x32_bf16 v[130:133], v[82:85], v[218:221], v[130:133]
	v_mfma_f32_16x16x32_bf16 v[142:145], v[158:161], v[146:149], v[142:145]
	v_mfma_f32_16x16x32_bf16 v[90:93], v[190:193], v[218:221], v[86:89]
	s_barrier
	s_add_i32 s70, s72, s29
	v_lshl_add_u64 v[86:87], v[174:175], 0, s[34:35]
	s_mov_b32 m0, s70
	ds_read_b128 v[194:197], v189 offset:49152
	ds_read_b128 v[198:201], v189 offset:50176
	ds_read_b128 v[202:205], v189 offset:51200
	ds_read_b128 v[210:213], v189 offset:52224
	ds_read_b128 v[214:217], v189 offset:53248
	ds_read_b128 v[218:221], v189 offset:54272
	ds_read_b128 v[222:225], v189 offset:55296
	ds_read_b128 v[242:245], v189 offset:56320
	global_load_lds_dwordx4 v[86:87], off
	s_add_i32 m0, s70, 0x2000
	s_add_u32 s70, s92, 0x40080
	v_lshl_add_u64 v[86:87], v[186:187], 0, s[34:35]
	s_addc_u32 s71, s93, 0
	s_add_i32 s72, s73, s29
	global_load_lds_dwordx4 v[86:87], off
	v_lshl_add_u64 v[86:87], s[70:71], 0, v[164:165]
	s_mov_b32 m0, s72
	s_nop 0
	global_load_lds_dwordx4 v[86:87], off
	v_lshl_add_u64 v[86:87], s[70:71], 0, v[168:169]
	s_add_i32 m0, s72, 0x2000
	s_nop 0
	global_load_lds_dwordx4 v[86:87], off
	v_lshl_add_u64 v[86:87], v[206:207], 0, s[34:35]
	s_mov_b32 m0, s19
	s_nop 0
	global_load_lds_dwordx4 v[86:87], off
	v_lshl_add_u64 v[86:87], v[226:227], 0, s[34:35]
	s_mov_b32 m0, s20
	s_nop 0
	global_load_lds_dwordx4 v[86:87], off
	s_waitcnt vmcnt(8)
	s_waitcnt lgkmcnt(0)
	s_barrier
	s_waitcnt lgkmcnt(0)
	v_mfma_f32_16x16x32_bf16 v[14:17], v[50:53], v[222:225], v[14:17]
	v_mfma_f32_16x16x32_bf16 v[86:89], v[74:77], v[242:245], v[14:17]
	v_mfma_f32_16x16x32_bf16 v[14:17], v[78:81], v[222:225], v[22:25]
	v_mfma_f32_16x16x32_bf16 v[146:149], v[82:85], v[242:245], v[14:17]
	v_mfma_f32_16x16x32_bf16 v[14:17], v[154:157], v[194:197], v[26:29]
	v_mfma_f32_16x16x32_bf16 v[70:73], v[50:53], v[194:197], v[70:73]
	v_mfma_f32_16x16x32_bf16 v[62:65], v[50:53], v[202:205], v[62:65]
	v_mfma_f32_16x16x32_bf16 v[42:45], v[50:53], v[214:217], v[42:45]
	v_mfma_f32_16x16x32_bf16 v[50:53], v[158:161], v[198:201], v[14:17]
	v_mfma_f32_16x16x32_bf16 v[14:17], v[182:185], v[194:197], v[46:49]
	v_mfma_f32_16x16x32_bf16 v[46:49], v[190:193], v[198:201], v[14:17]
	v_mfma_f32_16x16x32_bf16 v[14:17], v[154:157], v[202:205], v[34:37]
	v_mfma_f32_16x16x32_bf16 v[34:37], v[158:161], v[210:213], v[14:17]
	v_mfma_f32_16x16x32_bf16 v[14:17], v[182:185], v[202:205], v[30:33]
	v_mfma_f32_16x16x32_bf16 v[66:69], v[78:81], v[194:197], v[66:69]
	v_mfma_f32_16x16x32_bf16 v[54:57], v[78:81], v[202:205], v[54:57]
	v_mfma_f32_16x16x32_bf16 v[38:41], v[78:81], v[214:217], v[38:41]
	v_mfma_f32_16x16x32_bf16 v[30:33], v[190:193], v[210:213], v[14:17]
	v_mfma_f32_16x16x32_bf16 v[14:17], v[154:157], v[214:217], v[18:21]
	v_mfma_f32_16x16x32_bf16 v[10:13], v[182:185], v[214:217], v[10:13]
	v_mfma_f32_16x16x32_bf16 v[6:9], v[154:157], v[222:225], v[6:9]
	v_mfma_f32_16x16x32_bf16 v[2:5], v[182:185], v[222:225], v[2:5]
	v_mfma_f32_16x16x32_bf16 v[70:73], v[74:77], v[198:201], v[70:73]
	v_mfma_f32_16x16x32_bf16 v[66:69], v[82:85], v[198:201], v[66:69]
	v_mfma_f32_16x16x32_bf16 v[62:65], v[74:77], v[210:213], v[62:65]
	v_mfma_f32_16x16x32_bf16 v[54:57], v[82:85], v[210:213], v[54:57]
	v_mfma_f32_16x16x32_bf16 v[42:45], v[74:77], v[218:221], v[42:45]
	v_mfma_f32_16x16x32_bf16 v[38:41], v[82:85], v[218:221], v[38:41]
	v_mfma_f32_16x16x32_bf16 v[18:21], v[158:161], v[218:221], v[14:17]
	v_mfma_f32_16x16x32_bf16 v[10:13], v[190:193], v[218:221], v[10:13]
	v_mfma_f32_16x16x32_bf16 v[6:9], v[158:161], v[242:245], v[6:9]
	v_mfma_f32_16x16x32_bf16 v[2:5], v[190:193], v[242:245], v[2:5]
	s_barrier
	s_add_i32 s95, s95, 2
	s_add_u32 s42, s42, 0x100
	s_addc_u32 s43, s43, 0
	s_add_u32 s77, s77, 0x100
	s_addc_u32 s89, s89, 0
	s_cmp_gt_u32 s95, 13
	s_cbranch_scc0 .LBB0_243
	s_and_b64 vcc, exec, s[74:75]
	s_cbranch_vccz .LBB0_246
	s_barrier
